# v5
# speedup vs baseline: 1.0194x; 1.0194x over previous
; __device__ __forceinline__ uint32_t pack2(float a, float b) { return (uint32_t)f2bf(a) | ((uint32_t)f2bf(b) << 16); }
; __device__ __forceinline__ float lo2f(uint32_t u) { return __uint_as_float(u << 16); }
; __device__ __forceinline__ float hi2f(uint32_t u) { return __uint_as_float(u & 0xffff0000u); }
;     ...
;       for (int bj = 0; bj < 2; ++bj) for (int nn = 0; nn < 2; ++nn) {
;         const long tok = bcol + bj * HALF + wc * 32 + nn * 16 + efr;
;         float ss = 0.f;
;         for (int ai = 0; ai < 2; ++ai) for (int m = 0; m < 4; ++m) {
;           const f32x4 a = acc[ai][bj][m][nn];
;           const int n = brow + ai * HALF + wr * 64 + m * 16 + efq * 4;
;           uint2* pb = (uint2*)(outb + tok * DM + n);
;           const uint2 xo = *pb;
;           const float x0 = lo2f(xo.x) + a[0], x1 = hi2f(xo.x) + a[1], x2 = lo2f(xo.y) + a[2], x3 = hi2f(xo.y) + a[3];
;           if (ssq_out) {
;             uint2 pk; pk.x = pack2(x0, x1); pk.y = pack2(x2, x3);
;             *pb = pk;
;             const float r0 = lo2f(pk.x), r1 = hi2f(pk.x), r2 = lo2f(pk.y), r3 = hi2f(pk.y);
;             ss += r0 * r0 + r1 * r1 + r2 * r2 + r3 * r3;
;           } else {
;             *(float4*)(outf + tok * DM + n) = make_float4(x0, x1, x2, x3);
;           }
;         }
;         if (ssq_out) {
;           ss += __shfl_xor(ss, 16); ss += __shfl_xor(ss, 32);
;           if (efq == 0) ssq_out[tok * 8 + (brow >> 8) * 2 + wr] = ss;
;         }
.LBB0_93:
	s_and_b64 vcc, exec, s[26:27]
	s_cbranch_vccz .LBB0_53
	v_mov_b32_e32 v172, v132
	v_mov_b32_e32 v173, v133
	v_cmp_gt_u32_e64 s[12:13], 16, v140
	v_xor_b32_e32 v178, 16, v140
	v_lshlrev_b32_e32 v178, 2, v178
	v_xor_b32_e32 v179, 32, v140
	v_lshlrev_b32_e32 v179, 2, v179
	v_lshrrev_b32_e32 v162, 4, v140
	v_and_b32_e32 v163, 1, v162
	v_lshlrev_b32_e32 v163, 5, v163
	v_lshrrev_b32_e32 v162, 1, v162
	v_lshl_add_u32 v163, v162, 4, v163
	v_add_u32_e32 v162, s4, v214
	v_lshl_add_u32 v162, v162, 1, v163
	v_ashrrev_i32_e32 v163, 31, v162
	v_lshlrev_b64 v[164:165], 11, v[172:173]
	v_lshl_add_u64 v[164:165], s[78:79], 0, v[164:165]
	v_lshl_add_u64 v[162:163], v[164:165], 0, v[162:163]
	v_mov_b32_e32 v171, 0
	v_mov_b32_e32 v170, 0x8000
	v_lshl_add_u64 v[164:165], v[162:163], 0, v[170:171]
	v_mov_b32_e32 v170, 0x40000
	v_lshl_add_u64 v[166:167], v[162:163], 0, v[170:171]
	v_mov_b32_e32 v170, 0x48000
	v_lshl_add_u64 v[168:169], v[162:163], 0, v[170:171]
	global_load_dwordx4 v[130:133], v[162:163], off
	global_load_dwordx4 v[134:137], v[162:163], off offset:64
	global_load_dwordx4 v[138:141], v[162:163], off offset:256
	global_load_dwordx4 v[142:145], v[162:163], off offset:320
	global_load_dwordx4 v[146:149], v[164:165], off
	global_load_dwordx4 v[150:153], v[164:165], off offset:64
	global_load_dwordx4 v[154:157], v[164:165], off offset:256
	global_load_dwordx4 v[158:161], v[164:165], off offset:320
	s_ashr_i32 s0, s4, 7
	s_and_b32 s4, s0, -2
	s_ashr_i32 s5, s4, 31
	v_lshl_add_u64 v[174:175], s[4:5], 2, v[218:219]
	v_lshlrev_b64 v[176:177], 5, v[172:173]
	v_lshl_add_u64 v[174:175], v[174:175], 0, v[176:177]
	v_mov_b32_e32 v170, 0x1000
	v_lshl_add_u64 v[176:177], v[174:175], 0, v[170:171]
	s_waitcnt vmcnt(4)
	v_permlane16_swap_b32_e32 v130, v132
	v_permlane16_swap_b32_e32 v131, v133
	v_lshlrev_b32_e32 v184, 16, v130
	v_and_b32_e32 v185, 0xffff0000, v130
	v_lshlrev_b32_e32 v186, 16, v131
	v_and_b32_e32 v187, 0xffff0000, v131
	v_pk_add_f32 v[126:127], v[126:127], v[184:185]
	v_pk_add_f32 v[128:129], v[128:129], v[186:187]
	v_cvt_pk_bf16_f32 v130, v126, v127
	v_cvt_pk_bf16_f32 v131, v128, v129
	v_lshlrev_b32_e32 v188, 16, v130
	v_and_b32_e32 v189, 0xffff0000, v130
	v_lshlrev_b32_e32 v190, 16, v131
	v_and_b32_e32 v191, 0xffff0000, v131
	v_mul_f32_e32 v181, v189, v189
	v_fmac_f32_e32 v181, v188, v188
	v_fmac_f32_e32 v181, v190, v190
	v_fmac_f32_e32 v181, v191, v191
	v_mov_b32_e32 v180, v181
	v_lshlrev_b32_e32 v184, 16, v132
	v_and_b32_e32 v185, 0xffff0000, v132
	v_lshlrev_b32_e32 v186, 16, v133
	v_and_b32_e32 v187, 0xffff0000, v133
	v_pk_add_f32 v[122:123], v[122:123], v[184:185]
	v_pk_add_f32 v[124:125], v[124:125], v[186:187]
	v_cvt_pk_bf16_f32 v132, v122, v123
	v_cvt_pk_bf16_f32 v133, v124, v125
	v_lshlrev_b32_e32 v188, 16, v132
	v_and_b32_e32 v189, 0xffff0000, v132
	v_lshlrev_b32_e32 v190, 16, v133
	v_and_b32_e32 v191, 0xffff0000, v133
	v_mul_f32_e32 v181, v189, v189
	v_fmac_f32_e32 v181, v188, v188
	v_fmac_f32_e32 v181, v190, v190
	v_fmac_f32_e32 v181, v191, v191
	v_add_f32_e32 v180, v180, v181
	s_nop 0
	v_permlane16_swap_b32_e32 v130, v132
	v_permlane16_swap_b32_e32 v131, v133
	global_store_dwordx4 v[162:163], v[130:133], off
	v_permlane16_swap_b32_e32 v134, v136
	v_permlane16_swap_b32_e32 v135, v137
	v_lshlrev_b32_e32 v184, 16, v134
	v_and_b32_e32 v185, 0xffff0000, v134
	v_lshlrev_b32_e32 v186, 16, v135
	v_and_b32_e32 v187, 0xffff0000, v135
	v_pk_add_f32 v[118:119], v[118:119], v[184:185]
	v_pk_add_f32 v[120:121], v[120:121], v[186:187]
	v_cvt_pk_bf16_f32 v134, v118, v119
	v_cvt_pk_bf16_f32 v135, v120, v121
	v_lshlrev_b32_e32 v188, 16, v134
	v_and_b32_e32 v189, 0xffff0000, v134
	v_lshlrev_b32_e32 v190, 16, v135
	v_and_b32_e32 v191, 0xffff0000, v135
	v_mul_f32_e32 v181, v189, v189
	v_fmac_f32_e32 v181, v188, v188
	v_fmac_f32_e32 v181, v190, v190
	v_fmac_f32_e32 v181, v191, v191
	v_add_f32_e32 v180, v180, v181
	v_lshlrev_b32_e32 v184, 16, v136
	v_and_b32_e32 v185, 0xffff0000, v136
	v_lshlrev_b32_e32 v186, 16, v137
	v_and_b32_e32 v187, 0xffff0000, v137
	v_pk_add_f32 v[110:111], v[110:111], v[184:185]
	v_pk_add_f32 v[112:113], v[112:113], v[186:187]
	v_cvt_pk_bf16_f32 v136, v110, v111
	v_cvt_pk_bf16_f32 v137, v112, v113
	v_lshlrev_b32_e32 v188, 16, v136
	v_and_b32_e32 v189, 0xffff0000, v136
	v_lshlrev_b32_e32 v190, 16, v137
	v_and_b32_e32 v191, 0xffff0000, v137
	v_mul_f32_e32 v181, v189, v189
	v_fmac_f32_e32 v181, v188, v188
	v_fmac_f32_e32 v181, v190, v190
	v_fmac_f32_e32 v181, v191, v191
	v_add_f32_e32 v180, v180, v181
	s_nop 0
	v_permlane16_swap_b32_e32 v134, v136
	v_permlane16_swap_b32_e32 v135, v137
	global_store_dwordx4 v[162:163], v[134:137], off offset:64
	v_permlane16_swap_b32_e32 v138, v140
	v_permlane16_swap_b32_e32 v139, v141
	v_lshlrev_b32_e32 v184, 16, v138
	v_and_b32_e32 v185, 0xffff0000, v138
	v_lshlrev_b32_e32 v186, 16, v139
	v_and_b32_e32 v187, 0xffff0000, v139
	v_pk_add_f32 v[114:115], v[114:115], v[184:185]
	v_pk_add_f32 v[116:117], v[116:117], v[186:187]
	v_cvt_pk_bf16_f32 v138, v114, v115
	v_cvt_pk_bf16_f32 v139, v116, v117
	v_lshlrev_b32_e32 v188, 16, v138
	v_and_b32_e32 v189, 0xffff0000, v138
	v_lshlrev_b32_e32 v190, 16, v139
	v_and_b32_e32 v191, 0xffff0000, v139
	v_mul_f32_e32 v181, v189, v189
	v_fmac_f32_e32 v181, v188, v188
	v_fmac_f32_e32 v181, v190, v190
	v_fmac_f32_e32 v181, v191, v191
	v_add_f32_e32 v180, v180, v181
	v_lshlrev_b32_e32 v184, 16, v140
	v_and_b32_e32 v185, 0xffff0000, v140
	v_lshlrev_b32_e32 v186, 16, v141
	v_and_b32_e32 v187, 0xffff0000, v141
	v_pk_add_f32 v[106:107], v[106:107], v[184:185]
	v_pk_add_f32 v[108:109], v[108:109], v[186:187]
	v_cvt_pk_bf16_f32 v140, v106, v107
	v_cvt_pk_bf16_f32 v141, v108, v109
; __device__ __forceinline__ uint32_t pack2(float a, float b) { return (uint32_t)f2bf(a) | ((uint32_t)f2bf(b) << 16); }
; __device__ __forceinline__ float lo2f(uint32_t u) { return __uint_as_float(u << 16); }
; __device__ __forceinline__ float hi2f(uint32_t u) { return __uint_as_float(u & 0xffff0000u); }
;     ...
;       for (int bj = 0; bj < 2; ++bj) for (int nn = 0; nn < 2; ++nn) {
;         const long tok = bcol + bj * HALF + wc * 32 + nn * 16 + efr;
;         float ss = 0.f;
;         for (int ai = 0; ai < 2; ++ai) for (int m = 0; m < 4; ++m) {
;           const f32x4 a = acc[ai][bj][m][nn];
;           const int n = brow + ai * HALF + wr * 64 + m * 16 + efq * 4;
;           uint2* pb = (uint2*)(outb + tok * DM + n);
;           const uint2 xo = *pb;
;           const float x0 = lo2f(xo.x) + a[0], x1 = hi2f(xo.x) + a[1], x2 = lo2f(xo.y) + a[2], x3 = hi2f(xo.y) + a[3];
;           if (ssq_out) {
;             uint2 pk; pk.x = pack2(x0, x1); pk.y = pack2(x2, x3);
;             *pb = pk;
;             const float r0 = lo2f(pk.x), r1 = hi2f(pk.x), r2 = lo2f(pk.y), r3 = hi2f(pk.y);
;             ss += r0 * r0 + r1 * r1 + r2 * r2 + r3 * r3;
;           } else {
;             *(float4*)(outf + tok * DM + n) = make_float4(x0, x1, x2, x3);
;           }
;         }
;         if (ssq_out) {
;           ss += __shfl_xor(ss, 16); ss += __shfl_xor(ss, 32);
;           if (efq == 0) ssq_out[tok * 8 + (brow >> 8) * 2 + wr] = ss;
;         }
	v_lshlrev_b32_e32 v188, 16, v140
	v_and_b32_e32 v189, 0xffff0000, v140
	v_lshlrev_b32_e32 v190, 16, v141
	v_and_b32_e32 v191, 0xffff0000, v141
	v_mul_f32_e32 v181, v189, v189
	v_fmac_f32_e32 v181, v188, v188
	v_fmac_f32_e32 v181, v190, v190
	v_fmac_f32_e32 v181, v191, v191
	v_add_f32_e32 v180, v180, v181
	s_nop 0
	v_permlane16_swap_b32_e32 v138, v140
	v_permlane16_swap_b32_e32 v139, v141
	global_store_dwordx4 v[162:163], v[138:141], off offset:256
	v_permlane16_swap_b32_e32 v142, v144
	v_permlane16_swap_b32_e32 v143, v145
	v_lshlrev_b32_e32 v184, 16, v142
	v_and_b32_e32 v185, 0xffff0000, v142
	v_lshlrev_b32_e32 v186, 16, v143
	v_and_b32_e32 v187, 0xffff0000, v143
	v_pk_add_f32 v[102:103], v[102:103], v[184:185]
	v_pk_add_f32 v[104:105], v[104:105], v[186:187]
	v_cvt_pk_bf16_f32 v142, v102, v103
	v_cvt_pk_bf16_f32 v143, v104, v105
	v_lshlrev_b32_e32 v188, 16, v142
	v_and_b32_e32 v189, 0xffff0000, v142
	v_lshlrev_b32_e32 v190, 16, v143
	v_and_b32_e32 v191, 0xffff0000, v143
	v_mul_f32_e32 v181, v189, v189
	v_fmac_f32_e32 v181, v188, v188
	v_fmac_f32_e32 v181, v190, v190
	v_fmac_f32_e32 v181, v191, v191
	v_add_f32_e32 v180, v180, v181
	v_lshlrev_b32_e32 v184, 16, v144
	v_and_b32_e32 v185, 0xffff0000, v144
	v_lshlrev_b32_e32 v186, 16, v145
	v_and_b32_e32 v187, 0xffff0000, v145
	v_pk_add_f32 v[98:99], v[98:99], v[184:185]
	v_pk_add_f32 v[100:101], v[100:101], v[186:187]
	v_cvt_pk_bf16_f32 v144, v98, v99
	v_cvt_pk_bf16_f32 v145, v100, v101
	v_lshlrev_b32_e32 v188, 16, v144
	v_and_b32_e32 v189, 0xffff0000, v144
	v_lshlrev_b32_e32 v190, 16, v145
	v_and_b32_e32 v191, 0xffff0000, v145
	v_mul_f32_e32 v181, v189, v189
	v_fmac_f32_e32 v181, v188, v188
	v_fmac_f32_e32 v181, v190, v190
	v_fmac_f32_e32 v181, v191, v191
	v_add_f32_e32 v180, v180, v181
	s_nop 0
	v_permlane16_swap_b32_e32 v142, v144
	v_permlane16_swap_b32_e32 v143, v145
	global_store_dwordx4 v[162:163], v[142:145], off offset:320
	ds_bpermute_b32 v182, v178, v180
	s_waitcnt lgkmcnt(0)
	v_add_f32_e32 v180, v180, v182
	ds_bpermute_b32 v182, v179, v180
	s_waitcnt lgkmcnt(0)
	v_add_f32_e32 v180, v180, v182
	s_and_saveexec_b64 s[4:5], s[12:13]
	global_store_dword v[174:175], v180, off
	s_mov_b64 exec, s[4:5]
	global_load_dwordx4 v[130:133], v[166:167], off
	global_load_dwordx4 v[134:137], v[166:167], off offset:64
	global_load_dwordx4 v[138:141], v[166:167], off offset:256
	global_load_dwordx4 v[142:145], v[166:167], off offset:320
	s_waitcnt vmcnt(9)
	v_permlane16_swap_b32_e32 v146, v148
	v_permlane16_swap_b32_e32 v147, v149
	v_lshlrev_b32_e32 v184, 16, v146
	v_and_b32_e32 v185, 0xffff0000, v146
	v_lshlrev_b32_e32 v186, 16, v147
	v_and_b32_e32 v187, 0xffff0000, v147
	v_pk_add_f32 v[94:95], v[94:95], v[184:185]
	v_pk_add_f32 v[96:97], v[96:97], v[186:187]
	v_cvt_pk_bf16_f32 v146, v94, v95
	v_cvt_pk_bf16_f32 v147, v96, v97
	v_lshlrev_b32_e32 v188, 16, v146
	v_and_b32_e32 v189, 0xffff0000, v146
	v_lshlrev_b32_e32 v190, 16, v147
	v_and_b32_e32 v191, 0xffff0000, v147
	v_mul_f32_e32 v181, v189, v189
	v_fmac_f32_e32 v181, v188, v188
	v_fmac_f32_e32 v181, v190, v190
	v_fmac_f32_e32 v181, v191, v191
	v_mov_b32_e32 v180, v181
	v_lshlrev_b32_e32 v184, 16, v148
	v_and_b32_e32 v185, 0xffff0000, v148
	v_lshlrev_b32_e32 v186, 16, v149
	v_and_b32_e32 v187, 0xffff0000, v149
	v_pk_add_f32 v[90:91], v[90:91], v[184:185]
	v_pk_add_f32 v[92:93], v[92:93], v[186:187]
	v_cvt_pk_bf16_f32 v148, v90, v91
	v_cvt_pk_bf16_f32 v149, v92, v93
	v_lshlrev_b32_e32 v188, 16, v148
	v_and_b32_e32 v189, 0xffff0000, v148
	v_lshlrev_b32_e32 v190, 16, v149
	v_and_b32_e32 v191, 0xffff0000, v149
	v_mul_f32_e32 v181, v189, v189
	v_fmac_f32_e32 v181, v188, v188
	v_fmac_f32_e32 v181, v190, v190
	v_fmac_f32_e32 v181, v191, v191
	v_add_f32_e32 v180, v180, v181
	s_nop 0
	v_permlane16_swap_b32_e32 v146, v148
	v_permlane16_swap_b32_e32 v147, v149
	global_store_dwordx4 v[164:165], v[146:149], off
	v_permlane16_swap_b32_e32 v150, v152
	v_permlane16_swap_b32_e32 v151, v153
	v_lshlrev_b32_e32 v184, 16, v150
	v_and_b32_e32 v185, 0xffff0000, v150
	v_lshlrev_b32_e32 v186, 16, v151
	v_and_b32_e32 v187, 0xffff0000, v151
	v_pk_add_f32 v[86:87], v[86:87], v[184:185]
	v_pk_add_f32 v[88:89], v[88:89], v[186:187]
	v_cvt_pk_bf16_f32 v150, v86, v87
	v_cvt_pk_bf16_f32 v151, v88, v89
	v_lshlrev_b32_e32 v188, 16, v150
	v_and_b32_e32 v189, 0xffff0000, v150
	v_lshlrev_b32_e32 v190, 16, v151
	v_and_b32_e32 v191, 0xffff0000, v151
	v_mul_f32_e32 v181, v189, v189
	v_fmac_f32_e32 v181, v188, v188
	v_fmac_f32_e32 v181, v190, v190
	v_fmac_f32_e32 v181, v191, v191
	v_add_f32_e32 v180, v180, v181
	v_lshlrev_b32_e32 v184, 16, v152
	v_and_b32_e32 v185, 0xffff0000, v152
	v_lshlrev_b32_e32 v186, 16, v153
	v_and_b32_e32 v187, 0xffff0000, v153
	v_pk_add_f32 v[78:79], v[78:79], v[184:185]
	v_pk_add_f32 v[80:81], v[80:81], v[186:187]
	v_cvt_pk_bf16_f32 v152, v78, v79
	v_cvt_pk_bf16_f32 v153, v80, v81
	v_lshlrev_b32_e32 v188, 16, v152
	v_and_b32_e32 v189, 0xffff0000, v152
	v_lshlrev_b32_e32 v190, 16, v153
	v_and_b32_e32 v191, 0xffff0000, v153
	v_mul_f32_e32 v181, v189, v189
	v_fmac_f32_e32 v181, v188, v188
	v_fmac_f32_e32 v181, v190, v190
	v_fmac_f32_e32 v181, v191, v191
	v_add_f32_e32 v180, v180, v181
	s_nop 0
	v_permlane16_swap_b32_e32 v150, v152
	v_permlane16_swap_b32_e32 v151, v153
	global_store_dwordx4 v[164:165], v[150:153], off offset:64
	v_permlane16_swap_b32_e32 v154, v156
	v_permlane16_swap_b32_e32 v155, v157
	v_lshlrev_b32_e32 v184, 16, v154
	v_and_b32_e32 v185, 0xffff0000, v154
	v_lshlrev_b32_e32 v186, 16, v155
	v_and_b32_e32 v187, 0xffff0000, v155
	v_pk_add_f32 v[82:83], v[82:83], v[184:185]
	v_pk_add_f32 v[84:85], v[84:85], v[186:187]
	v_cvt_pk_bf16_f32 v154, v82, v83
; __device__ __forceinline__ uint32_t pack2(float a, float b) { return (uint32_t)f2bf(a) | ((uint32_t)f2bf(b) << 16); }
; __device__ __forceinline__ float lo2f(uint32_t u) { return __uint_as_float(u << 16); }
; __device__ __forceinline__ float hi2f(uint32_t u) { return __uint_as_float(u & 0xffff0000u); }
;     ...
;       for (int bj = 0; bj < 2; ++bj) for (int nn = 0; nn < 2; ++nn) {
;         const long tok = bcol + bj * HALF + wc * 32 + nn * 16 + efr;
;         float ss = 0.f;
;         for (int ai = 0; ai < 2; ++ai) for (int m = 0; m < 4; ++m) {
;           const f32x4 a = acc[ai][bj][m][nn];
;           const int n = brow + ai * HALF + wr * 64 + m * 16 + efq * 4;
;           uint2* pb = (uint2*)(outb + tok * DM + n);
;           const uint2 xo = *pb;
;           const float x0 = lo2f(xo.x) + a[0], x1 = hi2f(xo.x) + a[1], x2 = lo2f(xo.y) + a[2], x3 = hi2f(xo.y) + a[3];
;           if (ssq_out) {
;             uint2 pk; pk.x = pack2(x0, x1); pk.y = pack2(x2, x3);
;             *pb = pk;
;             const float r0 = lo2f(pk.x), r1 = hi2f(pk.x), r2 = lo2f(pk.y), r3 = hi2f(pk.y);
;             ss += r0 * r0 + r1 * r1 + r2 * r2 + r3 * r3;
;           } else {
;             *(float4*)(outf + tok * DM + n) = make_float4(x0, x1, x2, x3);
;           }
;         }
;         if (ssq_out) {
;           ss += __shfl_xor(ss, 16); ss += __shfl_xor(ss, 32);
;           if (efq == 0) ssq_out[tok * 8 + (brow >> 8) * 2 + wr] = ss;
;         }
	v_cvt_pk_bf16_f32 v155, v84, v85
	v_lshlrev_b32_e32 v188, 16, v154
	v_and_b32_e32 v189, 0xffff0000, v154
	v_lshlrev_b32_e32 v190, 16, v155
	v_and_b32_e32 v191, 0xffff0000, v155
	v_mul_f32_e32 v181, v189, v189
	v_fmac_f32_e32 v181, v188, v188
	v_fmac_f32_e32 v181, v190, v190
	v_fmac_f32_e32 v181, v191, v191
	v_add_f32_e32 v180, v180, v181
	v_lshlrev_b32_e32 v184, 16, v156
	v_and_b32_e32 v185, 0xffff0000, v156
	v_lshlrev_b32_e32 v186, 16, v157
	v_and_b32_e32 v187, 0xffff0000, v157
	v_pk_add_f32 v[74:75], v[74:75], v[184:185]
	v_pk_add_f32 v[76:77], v[76:77], v[186:187]
	v_cvt_pk_bf16_f32 v156, v74, v75
	v_cvt_pk_bf16_f32 v157, v76, v77
	v_lshlrev_b32_e32 v188, 16, v156
	v_and_b32_e32 v189, 0xffff0000, v156
	v_lshlrev_b32_e32 v190, 16, v157
	v_and_b32_e32 v191, 0xffff0000, v157
	v_mul_f32_e32 v181, v189, v189
	v_fmac_f32_e32 v181, v188, v188
	v_fmac_f32_e32 v181, v190, v190
	v_fmac_f32_e32 v181, v191, v191
	v_add_f32_e32 v180, v180, v181
	s_nop 0
	v_permlane16_swap_b32_e32 v154, v156
	v_permlane16_swap_b32_e32 v155, v157
	global_store_dwordx4 v[164:165], v[154:157], off offset:256
	v_permlane16_swap_b32_e32 v158, v160
	v_permlane16_swap_b32_e32 v159, v161
	v_lshlrev_b32_e32 v184, 16, v158
	v_and_b32_e32 v185, 0xffff0000, v158
	v_lshlrev_b32_e32 v186, 16, v159
	v_and_b32_e32 v187, 0xffff0000, v159
	v_pk_add_f32 v[70:71], v[70:71], v[184:185]
	v_pk_add_f32 v[72:73], v[72:73], v[186:187]
	v_cvt_pk_bf16_f32 v158, v70, v71
	v_cvt_pk_bf16_f32 v159, v72, v73
	v_lshlrev_b32_e32 v188, 16, v158
	v_and_b32_e32 v189, 0xffff0000, v158
	v_lshlrev_b32_e32 v190, 16, v159
	v_and_b32_e32 v191, 0xffff0000, v159
	v_mul_f32_e32 v181, v189, v189
	v_fmac_f32_e32 v181, v188, v188
	v_fmac_f32_e32 v181, v190, v190
	v_fmac_f32_e32 v181, v191, v191
	v_add_f32_e32 v180, v180, v181
	v_lshlrev_b32_e32 v184, 16, v160
	v_and_b32_e32 v185, 0xffff0000, v160
	v_lshlrev_b32_e32 v186, 16, v161
	v_and_b32_e32 v187, 0xffff0000, v161
	v_pk_add_f32 v[66:67], v[66:67], v[184:185]
	v_pk_add_f32 v[68:69], v[68:69], v[186:187]
	v_cvt_pk_bf16_f32 v160, v66, v67
	v_cvt_pk_bf16_f32 v161, v68, v69
	v_lshlrev_b32_e32 v188, 16, v160
	v_and_b32_e32 v189, 0xffff0000, v160
	v_lshlrev_b32_e32 v190, 16, v161
	v_and_b32_e32 v191, 0xffff0000, v161
	v_mul_f32_e32 v181, v189, v189
	v_fmac_f32_e32 v181, v188, v188
	v_fmac_f32_e32 v181, v190, v190
	v_fmac_f32_e32 v181, v191, v191
	v_add_f32_e32 v180, v180, v181
	s_nop 0
	v_permlane16_swap_b32_e32 v158, v160
	v_permlane16_swap_b32_e32 v159, v161
	global_store_dwordx4 v[164:165], v[158:161], off offset:320
	ds_bpermute_b32 v182, v178, v180
	s_waitcnt lgkmcnt(0)
	v_add_f32_e32 v180, v180, v182
	ds_bpermute_b32 v182, v179, v180
	s_waitcnt lgkmcnt(0)
	v_add_f32_e32 v180, v180, v182
	s_and_saveexec_b64 s[4:5], s[12:13]
	global_store_dword v[174:175], v180, off offset:512
	s_mov_b64 exec, s[4:5]
	global_load_dwordx4 v[146:149], v[168:169], off
	global_load_dwordx4 v[150:153], v[168:169], off offset:64
	global_load_dwordx4 v[154:157], v[168:169], off offset:256
	global_load_dwordx4 v[158:161], v[168:169], off offset:320
	s_waitcnt vmcnt(9)
	v_permlane16_swap_b32_e32 v130, v132
	v_permlane16_swap_b32_e32 v131, v133
	v_lshlrev_b32_e32 v184, 16, v130
	v_and_b32_e32 v185, 0xffff0000, v130
	v_lshlrev_b32_e32 v186, 16, v131
	v_and_b32_e32 v187, 0xffff0000, v131
	v_pk_add_f32 v[62:63], v[62:63], v[184:185]
	v_pk_add_f32 v[64:65], v[64:65], v[186:187]
	v_cvt_pk_bf16_f32 v130, v62, v63
	v_cvt_pk_bf16_f32 v131, v64, v65
	v_lshlrev_b32_e32 v188, 16, v130
	v_and_b32_e32 v189, 0xffff0000, v130
	v_lshlrev_b32_e32 v190, 16, v131
	v_and_b32_e32 v191, 0xffff0000, v131
	v_mul_f32_e32 v181, v189, v189
	v_fmac_f32_e32 v181, v188, v188
	v_fmac_f32_e32 v181, v190, v190
	v_fmac_f32_e32 v181, v191, v191
	v_mov_b32_e32 v180, v181
	v_lshlrev_b32_e32 v184, 16, v132
	v_and_b32_e32 v185, 0xffff0000, v132
	v_lshlrev_b32_e32 v186, 16, v133
	v_and_b32_e32 v187, 0xffff0000, v133
	v_pk_add_f32 v[58:59], v[58:59], v[184:185]
	v_pk_add_f32 v[60:61], v[60:61], v[186:187]
	v_cvt_pk_bf16_f32 v132, v58, v59
	v_cvt_pk_bf16_f32 v133, v60, v61
	v_lshlrev_b32_e32 v188, 16, v132
	v_and_b32_e32 v189, 0xffff0000, v132
	v_lshlrev_b32_e32 v190, 16, v133
	v_and_b32_e32 v191, 0xffff0000, v133
	v_mul_f32_e32 v181, v189, v189
	v_fmac_f32_e32 v181, v188, v188
	v_fmac_f32_e32 v181, v190, v190
	v_fmac_f32_e32 v181, v191, v191
	v_add_f32_e32 v180, v180, v181
	s_nop 0
	v_permlane16_swap_b32_e32 v130, v132
	v_permlane16_swap_b32_e32 v131, v133
	global_store_dwordx4 v[166:167], v[130:133], off
	v_permlane16_swap_b32_e32 v134, v136
	v_permlane16_swap_b32_e32 v135, v137
	v_lshlrev_b32_e32 v184, 16, v134
	v_and_b32_e32 v185, 0xffff0000, v134
	v_lshlrev_b32_e32 v186, 16, v135
	v_and_b32_e32 v187, 0xffff0000, v135
	v_pk_add_f32 v[54:55], v[54:55], v[184:185]
	v_pk_add_f32 v[56:57], v[56:57], v[186:187]
	v_cvt_pk_bf16_f32 v134, v54, v55
	v_cvt_pk_bf16_f32 v135, v56, v57
	v_lshlrev_b32_e32 v188, 16, v134
	v_and_b32_e32 v189, 0xffff0000, v134
	v_lshlrev_b32_e32 v190, 16, v135
	v_and_b32_e32 v191, 0xffff0000, v135
	v_mul_f32_e32 v181, v189, v189
	v_fmac_f32_e32 v181, v188, v188
	v_fmac_f32_e32 v181, v190, v190
	v_fmac_f32_e32 v181, v191, v191
	v_add_f32_e32 v180, v180, v181
	v_lshlrev_b32_e32 v184, 16, v136
	v_and_b32_e32 v185, 0xffff0000, v136
	v_lshlrev_b32_e32 v186, 16, v137
	v_and_b32_e32 v187, 0xffff0000, v137
	v_pk_add_f32 v[50:51], v[50:51], v[184:185]
	v_pk_add_f32 v[52:53], v[52:53], v[186:187]
	v_cvt_pk_bf16_f32 v136, v50, v51
	v_cvt_pk_bf16_f32 v137, v52, v53
	v_lshlrev_b32_e32 v188, 16, v136
	v_and_b32_e32 v189, 0xffff0000, v136
	v_lshlrev_b32_e32 v190, 16, v137
	v_and_b32_e32 v191, 0xffff0000, v137
; __device__ __forceinline__ uint32_t pack2(float a, float b) { return (uint32_t)f2bf(a) | ((uint32_t)f2bf(b) << 16); }
; __device__ __forceinline__ float lo2f(uint32_t u) { return __uint_as_float(u << 16); }
; __device__ __forceinline__ float hi2f(uint32_t u) { return __uint_as_float(u & 0xffff0000u); }
;     ...
;       for (int bj = 0; bj < 2; ++bj) for (int nn = 0; nn < 2; ++nn) {
;         const long tok = bcol + bj * HALF + wc * 32 + nn * 16 + efr;
;         float ss = 0.f;
;         for (int ai = 0; ai < 2; ++ai) for (int m = 0; m < 4; ++m) {
;           const f32x4 a = acc[ai][bj][m][nn];
;           const int n = brow + ai * HALF + wr * 64 + m * 16 + efq * 4;
;           uint2* pb = (uint2*)(outb + tok * DM + n);
;           const uint2 xo = *pb;
;           const float x0 = lo2f(xo.x) + a[0], x1 = hi2f(xo.x) + a[1], x2 = lo2f(xo.y) + a[2], x3 = hi2f(xo.y) + a[3];
;           if (ssq_out) {
;             uint2 pk; pk.x = pack2(x0, x1); pk.y = pack2(x2, x3);
;             *pb = pk;
;             const float r0 = lo2f(pk.x), r1 = hi2f(pk.x), r2 = lo2f(pk.y), r3 = hi2f(pk.y);
;             ss += r0 * r0 + r1 * r1 + r2 * r2 + r3 * r3;
;           } else {
;             *(float4*)(outf + tok * DM + n) = make_float4(x0, x1, x2, x3);
;           }
;         }
;         if (ssq_out) {
;           ss += __shfl_xor(ss, 16); ss += __shfl_xor(ss, 32);
;           if (efq == 0) ssq_out[tok * 8 + (brow >> 8) * 2 + wr] = ss;
;         }
	v_mul_f32_e32 v181, v189, v189
	v_fmac_f32_e32 v181, v188, v188
	v_fmac_f32_e32 v181, v190, v190
	v_fmac_f32_e32 v181, v191, v191
	v_add_f32_e32 v180, v180, v181
	s_nop 0
	v_permlane16_swap_b32_e32 v134, v136
	v_permlane16_swap_b32_e32 v135, v137
	global_store_dwordx4 v[166:167], v[134:137], off offset:64
	v_permlane16_swap_b32_e32 v138, v140
	v_permlane16_swap_b32_e32 v139, v141
	v_lshlrev_b32_e32 v184, 16, v138
	v_and_b32_e32 v185, 0xffff0000, v138
	v_lshlrev_b32_e32 v186, 16, v139
	v_and_b32_e32 v187, 0xffff0000, v139
	v_pk_add_f32 v[46:47], v[46:47], v[184:185]
	v_pk_add_f32 v[48:49], v[48:49], v[186:187]
	v_cvt_pk_bf16_f32 v138, v46, v47
	v_cvt_pk_bf16_f32 v139, v48, v49
	v_lshlrev_b32_e32 v188, 16, v138
	v_and_b32_e32 v189, 0xffff0000, v138
	v_lshlrev_b32_e32 v190, 16, v139
	v_and_b32_e32 v191, 0xffff0000, v139
	v_mul_f32_e32 v181, v189, v189
	v_fmac_f32_e32 v181, v188, v188
	v_fmac_f32_e32 v181, v190, v190
	v_fmac_f32_e32 v181, v191, v191
	v_add_f32_e32 v180, v180, v181
	v_lshlrev_b32_e32 v184, 16, v140
	v_and_b32_e32 v185, 0xffff0000, v140
	v_lshlrev_b32_e32 v186, 16, v141
	v_and_b32_e32 v187, 0xffff0000, v141
	v_pk_add_f32 v[42:43], v[42:43], v[184:185]
	v_pk_add_f32 v[44:45], v[44:45], v[186:187]
	v_cvt_pk_bf16_f32 v140, v42, v43
	v_cvt_pk_bf16_f32 v141, v44, v45
	v_lshlrev_b32_e32 v188, 16, v140
	v_and_b32_e32 v189, 0xffff0000, v140
	v_lshlrev_b32_e32 v190, 16, v141
	v_and_b32_e32 v191, 0xffff0000, v141
	v_mul_f32_e32 v181, v189, v189
	v_fmac_f32_e32 v181, v188, v188
	v_fmac_f32_e32 v181, v190, v190
	v_fmac_f32_e32 v181, v191, v191
	v_add_f32_e32 v180, v180, v181
	s_nop 0
	v_permlane16_swap_b32_e32 v138, v140
	v_permlane16_swap_b32_e32 v139, v141
	global_store_dwordx4 v[166:167], v[138:141], off offset:256
	v_permlane16_swap_b32_e32 v142, v144
	v_permlane16_swap_b32_e32 v143, v145
	v_lshlrev_b32_e32 v184, 16, v142
	v_and_b32_e32 v185, 0xffff0000, v142
	v_lshlrev_b32_e32 v186, 16, v143
	v_and_b32_e32 v187, 0xffff0000, v143
	v_pk_add_f32 v[38:39], v[38:39], v[184:185]
	v_pk_add_f32 v[40:41], v[40:41], v[186:187]
	v_cvt_pk_bf16_f32 v142, v38, v39
	v_cvt_pk_bf16_f32 v143, v40, v41
	v_lshlrev_b32_e32 v188, 16, v142
	v_and_b32_e32 v189, 0xffff0000, v142
	v_lshlrev_b32_e32 v190, 16, v143
	v_and_b32_e32 v191, 0xffff0000, v143
	v_mul_f32_e32 v181, v189, v189
	v_fmac_f32_e32 v181, v188, v188
	v_fmac_f32_e32 v181, v190, v190
	v_fmac_f32_e32 v181, v191, v191
	v_add_f32_e32 v180, v180, v181
	v_lshlrev_b32_e32 v184, 16, v144
	v_and_b32_e32 v185, 0xffff0000, v144
	v_lshlrev_b32_e32 v186, 16, v145
	v_and_b32_e32 v187, 0xffff0000, v145
	v_pk_add_f32 v[34:35], v[34:35], v[184:185]
	v_pk_add_f32 v[36:37], v[36:37], v[186:187]
	v_cvt_pk_bf16_f32 v144, v34, v35
	v_cvt_pk_bf16_f32 v145, v36, v37
	v_lshlrev_b32_e32 v188, 16, v144
	v_and_b32_e32 v189, 0xffff0000, v144
	v_lshlrev_b32_e32 v190, 16, v145
	v_and_b32_e32 v191, 0xffff0000, v145
	v_mul_f32_e32 v181, v189, v189
	v_fmac_f32_e32 v181, v188, v188
	v_fmac_f32_e32 v181, v190, v190
	v_fmac_f32_e32 v181, v191, v191
	v_add_f32_e32 v180, v180, v181
	s_nop 0
	v_permlane16_swap_b32_e32 v142, v144
	v_permlane16_swap_b32_e32 v143, v145
	global_store_dwordx4 v[166:167], v[142:145], off offset:320
	ds_bpermute_b32 v182, v178, v180
	s_waitcnt lgkmcnt(0)
	v_add_f32_e32 v180, v180, v182
	ds_bpermute_b32 v182, v179, v180
	s_waitcnt lgkmcnt(0)
	v_add_f32_e32 v180, v180, v182
	s_and_saveexec_b64 s[4:5], s[12:13]
	global_store_dword v[176:177], v180, off
	s_mov_b64 exec, s[4:5]
	s_waitcnt vmcnt(5)
; __device__ __forceinline__ uint32_t pack2(float a, float b) { return (uint32_t)f2bf(a) | ((uint32_t)f2bf(b) << 16); }
; __device__ __forceinline__ float lo2f(uint32_t u) { return __uint_as_float(u << 16); }
; __device__ __forceinline__ float hi2f(uint32_t u) { return __uint_as_float(u & 0xffff0000u); }
;     ...
;       for (int bj = 0; bj < 2; ++bj) for (int nn = 0; nn < 2; ++nn) {
;         const long tok = bcol + bj * HALF + wc * 32 + nn * 16 + efr;
;         float ss = 0.f;
;         for (int ai = 0; ai < 2; ++ai) for (int m = 0; m < 4; ++m) {
;           const f32x4 a = acc[ai][bj][m][nn];
;           const int n = brow + ai * HALF + wr * 64 + m * 16 + efq * 4;
;           uint2* pb = (uint2*)(outb + tok * DM + n);
;           const uint2 xo = *pb;
;           const float x0 = lo2f(xo.x) + a[0], x1 = hi2f(xo.x) + a[1], x2 = lo2f(xo.y) + a[2], x3 = hi2f(xo.y) + a[3];
;           if (ssq_out) {
;             uint2 pk; pk.x = pack2(x0, x1); pk.y = pack2(x2, x3);
;             *pb = pk;
;             const float r0 = lo2f(pk.x), r1 = hi2f(pk.x), r2 = lo2f(pk.y), r3 = hi2f(pk.y);
;             ss += r0 * r0 + r1 * r1 + r2 * r2 + r3 * r3;
;           } else {
;             *(float4*)(outf + tok * DM + n) = make_float4(x0, x1, x2, x3);
;           }
;         }
;         if (ssq_out) {
;           ss += __shfl_xor(ss, 16); ss += __shfl_xor(ss, 32);
;           if (efq == 0) ssq_out[tok * 8 + (brow >> 8) * 2 + wr] = ss;
;         }
	v_permlane16_swap_b32_e32 v146, v148
	v_permlane16_swap_b32_e32 v147, v149
	v_lshlrev_b32_e32 v184, 16, v146
	v_and_b32_e32 v185, 0xffff0000, v146
	v_lshlrev_b32_e32 v186, 16, v147
	v_and_b32_e32 v187, 0xffff0000, v147
	v_pk_add_f32 v[30:31], v[30:31], v[184:185]
	v_pk_add_f32 v[32:33], v[32:33], v[186:187]
	v_cvt_pk_bf16_f32 v146, v30, v31
	v_cvt_pk_bf16_f32 v147, v32, v33
	v_lshlrev_b32_e32 v188, 16, v146
	v_and_b32_e32 v189, 0xffff0000, v146
	v_lshlrev_b32_e32 v190, 16, v147
	v_and_b32_e32 v191, 0xffff0000, v147
	v_mul_f32_e32 v181, v189, v189
	v_fmac_f32_e32 v181, v188, v188
	v_fmac_f32_e32 v181, v190, v190
	v_fmac_f32_e32 v181, v191, v191
	v_mov_b32_e32 v180, v181
	v_lshlrev_b32_e32 v184, 16, v148
	v_and_b32_e32 v185, 0xffff0000, v148
	v_lshlrev_b32_e32 v186, 16, v149
	v_and_b32_e32 v187, 0xffff0000, v149
	v_pk_add_f32 v[26:27], v[26:27], v[184:185]
	v_pk_add_f32 v[28:29], v[28:29], v[186:187]
	v_cvt_pk_bf16_f32 v148, v26, v27
	v_cvt_pk_bf16_f32 v149, v28, v29
	v_lshlrev_b32_e32 v188, 16, v148
	v_and_b32_e32 v189, 0xffff0000, v148
	v_lshlrev_b32_e32 v190, 16, v149
	v_and_b32_e32 v191, 0xffff0000, v149
	v_mul_f32_e32 v181, v189, v189
	v_fmac_f32_e32 v181, v188, v188
	v_fmac_f32_e32 v181, v190, v190
	v_fmac_f32_e32 v181, v191, v191
	v_add_f32_e32 v180, v180, v181
	s_nop 0
	v_permlane16_swap_b32_e32 v146, v148
	v_permlane16_swap_b32_e32 v147, v149
	global_store_dwordx4 v[168:169], v[146:149], off
	v_permlane16_swap_b32_e32 v150, v152
	v_permlane16_swap_b32_e32 v151, v153
	v_lshlrev_b32_e32 v184, 16, v150
	v_and_b32_e32 v185, 0xffff0000, v150
	v_lshlrev_b32_e32 v186, 16, v151
	v_and_b32_e32 v187, 0xffff0000, v151
	v_pk_add_f32 v[22:23], v[22:23], v[184:185]
	v_pk_add_f32 v[24:25], v[24:25], v[186:187]
	v_cvt_pk_bf16_f32 v150, v22, v23
	v_cvt_pk_bf16_f32 v151, v24, v25
	v_lshlrev_b32_e32 v188, 16, v150
	v_and_b32_e32 v189, 0xffff0000, v150
	v_lshlrev_b32_e32 v190, 16, v151
	v_and_b32_e32 v191, 0xffff0000, v151
	v_mul_f32_e32 v181, v189, v189
	v_fmac_f32_e32 v181, v188, v188
	v_fmac_f32_e32 v181, v190, v190
	v_fmac_f32_e32 v181, v191, v191
	v_add_f32_e32 v180, v180, v181
	v_lshlrev_b32_e32 v184, 16, v152
	v_and_b32_e32 v185, 0xffff0000, v152
	v_lshlrev_b32_e32 v186, 16, v153
	v_and_b32_e32 v187, 0xffff0000, v153
	v_pk_add_f32 v[18:19], v[18:19], v[184:185]
	v_pk_add_f32 v[20:21], v[20:21], v[186:187]
	v_cvt_pk_bf16_f32 v152, v18, v19
	v_cvt_pk_bf16_f32 v153, v20, v21
	v_lshlrev_b32_e32 v188, 16, v152
	v_and_b32_e32 v189, 0xffff0000, v152
	v_lshlrev_b32_e32 v190, 16, v153
	v_and_b32_e32 v191, 0xffff0000, v153
	v_mul_f32_e32 v181, v189, v189
	v_fmac_f32_e32 v181, v188, v188
	v_fmac_f32_e32 v181, v190, v190
	v_fmac_f32_e32 v181, v191, v191
	v_add_f32_e32 v180, v180, v181
	s_nop 0
	v_permlane16_swap_b32_e32 v150, v152
	v_permlane16_swap_b32_e32 v151, v153
	global_store_dwordx4 v[168:169], v[150:153], off offset:64
	v_permlane16_swap_b32_e32 v154, v156
	v_permlane16_swap_b32_e32 v155, v157
	v_lshlrev_b32_e32 v184, 16, v154
	v_and_b32_e32 v185, 0xffff0000, v154
	v_lshlrev_b32_e32 v186, 16, v155
	v_and_b32_e32 v187, 0xffff0000, v155
	v_pk_add_f32 v[14:15], v[14:15], v[184:185]
	v_pk_add_f32 v[16:17], v[16:17], v[186:187]
	v_cvt_pk_bf16_f32 v154, v14, v15
	v_cvt_pk_bf16_f32 v155, v16, v17
	v_lshlrev_b32_e32 v188, 16, v154
	v_and_b32_e32 v189, 0xffff0000, v154
	v_lshlrev_b32_e32 v190, 16, v155
	v_and_b32_e32 v191, 0xffff0000, v155
	v_mul_f32_e32 v181, v189, v189
	v_fmac_f32_e32 v181, v188, v188
	v_fmac_f32_e32 v181, v190, v190
	v_fmac_f32_e32 v181, v191, v191
	v_add_f32_e32 v180, v180, v181
	v_lshlrev_b32_e32 v184, 16, v156
	v_and_b32_e32 v185, 0xffff0000, v156
	v_lshlrev_b32_e32 v186, 16, v157
	v_and_b32_e32 v187, 0xffff0000, v157
	v_pk_add_f32 v[10:11], v[10:11], v[184:185]
	v_pk_add_f32 v[12:13], v[12:13], v[186:187]
	v_cvt_pk_bf16_f32 v156, v10, v11
	v_cvt_pk_bf16_f32 v157, v12, v13
	v_lshlrev_b32_e32 v188, 16, v156
	v_and_b32_e32 v189, 0xffff0000, v156
	v_lshlrev_b32_e32 v190, 16, v157
	v_and_b32_e32 v191, 0xffff0000, v157
	v_mul_f32_e32 v181, v189, v189
	v_fmac_f32_e32 v181, v188, v188
	v_fmac_f32_e32 v181, v190, v190
	v_fmac_f32_e32 v181, v191, v191
	v_add_f32_e32 v180, v180, v181
	s_nop 0
	v_permlane16_swap_b32_e32 v154, v156
	v_permlane16_swap_b32_e32 v155, v157
	global_store_dwordx4 v[168:169], v[154:157], off offset:256
	v_permlane16_swap_b32_e32 v158, v160
	v_permlane16_swap_b32_e32 v159, v161
	v_lshlrev_b32_e32 v184, 16, v158
	v_and_b32_e32 v185, 0xffff0000, v158
	v_lshlrev_b32_e32 v186, 16, v159
	v_and_b32_e32 v187, 0xffff0000, v159
	v_pk_add_f32 v[6:7], v[6:7], v[184:185]
	v_pk_add_f32 v[8:9], v[8:9], v[186:187]
	v_cvt_pk_bf16_f32 v158, v6, v7
	v_cvt_pk_bf16_f32 v159, v8, v9
	v_lshlrev_b32_e32 v188, 16, v158
	v_and_b32_e32 v189, 0xffff0000, v158
	v_lshlrev_b32_e32 v190, 16, v159
	v_and_b32_e32 v191, 0xffff0000, v159
	v_mul_f32_e32 v181, v189, v189
	v_fmac_f32_e32 v181, v188, v188
	v_fmac_f32_e32 v181, v190, v190
	v_fmac_f32_e32 v181, v191, v191
	v_add_f32_e32 v180, v180, v181
	v_lshlrev_b32_e32 v184, 16, v160
	v_and_b32_e32 v185, 0xffff0000, v160
	v_lshlrev_b32_e32 v186, 16, v161
	v_and_b32_e32 v187, 0xffff0000, v161
	v_pk_add_f32 v[2:3], v[2:3], v[184:185]
	v_pk_add_f32 v[4:5], v[4:5], v[186:187]
	v_cvt_pk_bf16_f32 v160, v2, v3
	v_cvt_pk_bf16_f32 v161, v4, v5
	v_lshlrev_b32_e32 v188, 16, v160
	v_and_b32_e32 v189, 0xffff0000, v160
	v_lshlrev_b32_e32 v190, 16, v161
	v_and_b32_e32 v191, 0xffff0000, v161
	v_mul_f32_e32 v181, v189, v189
	v_fmac_f32_e32 v181, v188, v188
	v_fmac_f32_e32 v181, v190, v190
	v_fmac_f32_e32 v181, v191, v191
	v_add_f32_e32 v180, v180, v181
	s_nop 0
	v_permlane16_swap_b32_e32 v158, v160
	v_permlane16_swap_b32_e32 v159, v161
	global_store_dwordx4 v[168:169], v[158:161], off offset:320
	ds_bpermute_b32 v182, v178, v180
	s_waitcnt lgkmcnt(0)
	v_add_f32_e32 v180, v180, v182
	ds_bpermute_b32 v182, v179, v180
	s_waitcnt lgkmcnt(0)
	v_add_f32_e32 v180, v180, v182
	s_and_saveexec_b64 s[4:5], s[12:13]
	global_store_dword v[176:177], v180, off offset:512
	s_mov_b64 exec, s[4:5]
	s_branch .LBB0_53

; __device__ __forceinline__ uint32_t pack2(float a, float b) { return (uint32_t)f2bf(a) | ((uint32_t)f2bf(b) << 16); }
; __device__ __forceinline__ float rstd8(const float* q) {
;   const float4 a = *(const float4*)q, b = *(const float4*)(q + 4);
;   return rsqrtf((((a.x + a.y) + (a.z + a.w)) + ((b.x + b.y) + (b.z + b.w))) * (1.f / DM) + EPS);
; }
;     ...
;       for (int bj = 0; bj < 2; ++bj) for (int nn = 0; nn < 2; ++nn) {
;         const long tok = bcol + bj * HALF + wc * 32 + nn * 16 + efr;
;         const float rs = rstd8(ssq_in + tok * 8);
;         for (int ai = 0; ai < 2; ++ai) for (int m = 0; m < 4; ++m) {
;           f32x4 a = acc[ai][bj][m][nn];
;           const int n = brow + ai * HALF + wr * 64 + m * 16 + efq * 4;
;           for (int j = 0; j < 4; ++j) a[j] *= rs;
;           if (EPI == EPI_SQRELU) { for (int j = 0; j < 4; ++j) { float r = fmaxf(a[j], 0.f); a[j] = r * r; } }
;           if (EPI == EPI_INPROJ && brow >= ZXLD) {
;             if (n < ZXLD + 32) *(float4*)(outf + tok * 32 + (n - ZXLD)) = make_float4(a[0], a[1], a[2], a[3]);
;           } else {
;             uint2 pk; pk.x = pack2(a[0], a[1]); pk.y = pack2(a[2], a[3]);
;             *(uint2*)(outb + tok * ldo + n) = pk;
;           }
;         }
.LBB0_1125:
	s_or_b64 exec, exec, s[18:19]
	s_cmpk_lt_i32 s12, 0x1800
	s_cbranch_scc0 .Lmy_inproj_slow
	v_and_b32_e32 v131, 15, v0
	v_add3_u32 v132, s10, v201, v131
	v_ashrrev_i32_e32 v133, 31, v132
	v_lshlrev_b64 v[134:135], 5, v[132:133]
	v_lshl_add_u64 v[134:135], s[20:21], 0, v[134:135]
	v_add_u32_e32 v136, 0x80, v132
	v_ashrrev_i32_e32 v137, 31, v136
	v_lshlrev_b64 v[136:137], 5, v[136:137]
	v_lshl_add_u64 v[136:137], s[20:21], 0, v[136:137]
	global_load_dwordx4 v[150:153], v[134:135], off
	global_load_dwordx4 v[154:157], v[134:135], off offset:16
	global_load_dwordx4 v[158:161], v[134:135], off offset:512
	global_load_dwordx4 v[162:165], v[134:135], off offset:528
	global_load_dwordx4 v[166:169], v[136:137], off
	global_load_dwordx4 v[170:173], v[136:137], off offset:16
	global_load_dwordx4 v[174:177], v[136:137], off offset:512
	global_load_dwordx4 v[178:181], v[136:137], off offset:528
	v_lshrrev_b32_e32 v138, 4, v0
	v_and_b32_e32 v139, 1, v138
	v_lshlrev_b32_e32 v139, 5, v139
	v_lshrrev_b32_e32 v138, 1, v138
	v_lshl_add_u32 v139, v138, 4, v139
	v_add_u32_e32 v138, s12, v200
	v_lshl_add_u32 v138, v138, 1, v139
	v_ashrrev_i32_e32 v139, 31, v138
	v_mov_b64_e32 v[140:141], s[80:81]
	v_mad_i64_i32 v[140:141], vcc, v132, s3, v[140:141]
	v_lshl_add_u64 v[140:141], v[140:141], 0, v[138:139]
	v_mov_b32_e32 v149, 0
	v_mov_b32_e32 v148, 0x30000
	v_lshl_add_u64 v[142:143], v[140:141], 0, v[148:149]
	v_mov_b32_e32 v148, 0x180000
	v_lshl_add_u64 v[144:145], v[140:141], 0, v[148:149]
	v_mov_b32_e32 v148, 0x1b0000
	v_lshl_add_u64 v[146:147], v[140:141], 0, v[148:149]
	v_mov_b32_e32 v190, 0x358637bd
	s_waitcnt vmcnt(0)
	v_add_f32_e32 v150, v150, v151
	v_add_f32_e32 v152, v152, v153
	v_add_f32_e32 v154, v154, v155
	v_add_f32_e32 v156, v156, v157
	v_add_f32_e32 v150, v150, v152
	v_add_f32_e32 v154, v154, v156
	v_add_f32_e32 v150, v150, v154
	v_fmamk_f32 v150, v150, 0x3a800000, v190
	v_add_f32_e32 v158, v158, v159
	v_add_f32_e32 v160, v160, v161
	v_add_f32_e32 v162, v162, v163
	v_add_f32_e32 v164, v164, v165
	v_add_f32_e32 v158, v158, v160
	v_add_f32_e32 v162, v162, v164
	v_add_f32_e32 v158, v158, v162
	v_fmamk_f32 v158, v158, 0x3a800000, v190
	v_add_f32_e32 v166, v166, v167
	v_add_f32_e32 v168, v168, v169
	v_add_f32_e32 v170, v170, v171
	v_add_f32_e32 v172, v172, v173
	v_add_f32_e32 v166, v166, v168
	v_add_f32_e32 v170, v170, v172
	v_add_f32_e32 v166, v166, v170
	v_fmamk_f32 v166, v166, 0x3a800000, v190
	v_add_f32_e32 v174, v174, v175
	v_add_f32_e32 v176, v176, v177
	v_add_f32_e32 v178, v178, v179
	v_add_f32_e32 v180, v180, v181
	v_add_f32_e32 v174, v174, v176
	v_add_f32_e32 v178, v178, v180
	v_add_f32_e32 v174, v174, v178
	v_fmamk_f32 v174, v174, 0x3a800000, v190
	v_rsq_f32_e32 v182, v150
	v_rsq_f32_e32 v184, v158
	v_rsq_f32_e32 v186, v166
	v_rsq_f32_e32 v188, v174
	v_pk_mul_f32 v[126:127], v[126:127], v[182:183] op_sel_hi:[1,0]
	v_pk_mul_f32 v[128:129], v[128:129], v[182:183] op_sel_hi:[1,0]
	v_pk_mul_f32 v[122:123], v[122:123], v[182:183] op_sel_hi:[1,0]
	v_pk_mul_f32 v[124:125], v[124:125], v[182:183] op_sel_hi:[1,0]
	v_cvt_pk_bf16_f32 v192, v126, v127
	v_cvt_pk_bf16_f32 v193, v128, v129
	v_cvt_pk_bf16_f32 v194, v122, v123
	v_cvt_pk_bf16_f32 v195, v124, v125
	s_nop 1
	v_permlane16_swap_b32_e32 v192, v194
	v_permlane16_swap_b32_e32 v193, v195
	global_store_dwordx4 v[140:141], v[192:195], off
	v_pk_mul_f32 v[114:115], v[114:115], v[182:183] op_sel_hi:[1,0]
	v_pk_mul_f32 v[116:117], v[116:117], v[182:183] op_sel_hi:[1,0]
	v_pk_mul_f32 v[106:107], v[106:107], v[182:183] op_sel_hi:[1,0]
	v_pk_mul_f32 v[108:109], v[108:109], v[182:183] op_sel_hi:[1,0]
	v_cvt_pk_bf16_f32 v130, v114, v115
	v_cvt_pk_bf16_f32 v131, v116, v117
	v_cvt_pk_bf16_f32 v132, v106, v107
	v_cvt_pk_bf16_f32 v133, v108, v109
	s_nop 1
	v_permlane16_swap_b32_e32 v130, v132
	v_permlane16_swap_b32_e32 v131, v133
	global_store_dwordx4 v[140:141], v[130:133], off offset:64
	v_pk_mul_f32 v[118:119], v[118:119], v[182:183] op_sel_hi:[1,0]
	v_pk_mul_f32 v[120:121], v[120:121], v[182:183] op_sel_hi:[1,0]
	v_pk_mul_f32 v[110:111], v[110:111], v[182:183] op_sel_hi:[1,0]
	v_pk_mul_f32 v[112:113], v[112:113], v[182:183] op_sel_hi:[1,0]
	v_cvt_pk_bf16_f32 v192, v118, v119
	v_cvt_pk_bf16_f32 v193, v120, v121
	v_cvt_pk_bf16_f32 v194, v110, v111
	v_cvt_pk_bf16_f32 v195, v112, v113
	s_nop 1
	v_permlane16_swap_b32_e32 v192, v194
	v_permlane16_swap_b32_e32 v193, v195
	global_store_dwordx4 v[140:141], v[192:195], off offset:256
	v_pk_mul_f32 v[102:103], v[102:103], v[182:183] op_sel_hi:[1,0]
	v_pk_mul_f32 v[104:105], v[104:105], v[182:183] op_sel_hi:[1,0]
	v_pk_mul_f32 v[98:99], v[98:99], v[182:183] op_sel_hi:[1,0]
	v_pk_mul_f32 v[100:101], v[100:101], v[182:183] op_sel_hi:[1,0]
	v_cvt_pk_bf16_f32 v130, v102, v103
	v_cvt_pk_bf16_f32 v131, v104, v105
	v_cvt_pk_bf16_f32 v132, v98, v99
	v_cvt_pk_bf16_f32 v133, v100, v101
	s_nop 1
	v_permlane16_swap_b32_e32 v130, v132
	v_permlane16_swap_b32_e32 v131, v133
	global_store_dwordx4 v[140:141], v[130:133], off offset:320
	v_pk_mul_f32 v[94:95], v[94:95], v[184:185] op_sel_hi:[1,0]
	v_pk_mul_f32 v[96:97], v[96:97], v[184:185] op_sel_hi:[1,0]
	v_pk_mul_f32 v[90:91], v[90:91], v[184:185] op_sel_hi:[1,0]
	v_pk_mul_f32 v[92:93], v[92:93], v[184:185] op_sel_hi:[1,0]
	v_cvt_pk_bf16_f32 v192, v94, v95
	v_cvt_pk_bf16_f32 v193, v96, v97
	v_cvt_pk_bf16_f32 v194, v90, v91
	v_cvt_pk_bf16_f32 v195, v92, v93
	s_nop 1
	v_permlane16_swap_b32_e32 v192, v194
	v_permlane16_swap_b32_e32 v193, v195
	global_store_dwordx4 v[142:143], v[192:195], off
	v_pk_mul_f32 v[82:83], v[82:83], v[184:185] op_sel_hi:[1,0]
	v_pk_mul_f32 v[84:85], v[84:85], v[184:185] op_sel_hi:[1,0]
; __device__ __forceinline__ uint32_t pack2(float a, float b) { return (uint32_t)f2bf(a) | ((uint32_t)f2bf(b) << 16); }
;     ...
;       for (int bj = 0; bj < 2; ++bj) for (int nn = 0; nn < 2; ++nn) {
;         const long tok = bcol + bj * HALF + wc * 32 + nn * 16 + efr;
;         const float rs = rstd8(ssq_in + tok * 8);
;         for (int ai = 0; ai < 2; ++ai) for (int m = 0; m < 4; ++m) {
;           f32x4 a = acc[ai][bj][m][nn];
;           const int n = brow + ai * HALF + wr * 64 + m * 16 + efq * 4;
;           for (int j = 0; j < 4; ++j) a[j] *= rs;
;           if (EPI == EPI_SQRELU) { for (int j = 0; j < 4; ++j) { float r = fmaxf(a[j], 0.f); a[j] = r * r; } }
;           if (EPI == EPI_INPROJ && brow >= ZXLD) {
;             if (n < ZXLD + 32) *(float4*)(outf + tok * 32 + (n - ZXLD)) = make_float4(a[0], a[1], a[2], a[3]);
;           } else {
;             uint2 pk; pk.x = pack2(a[0], a[1]); pk.y = pack2(a[2], a[3]);
;             *(uint2*)(outb + tok * ldo + n) = pk;
;           }
;         }
	v_pk_mul_f32 v[74:75], v[74:75], v[184:185] op_sel_hi:[1,0]
	v_pk_mul_f32 v[76:77], v[76:77], v[184:185] op_sel_hi:[1,0]
	v_cvt_pk_bf16_f32 v130, v82, v83
	v_cvt_pk_bf16_f32 v131, v84, v85
	v_cvt_pk_bf16_f32 v132, v74, v75
	v_cvt_pk_bf16_f32 v133, v76, v77
	s_nop 1
	v_permlane16_swap_b32_e32 v130, v132
	v_permlane16_swap_b32_e32 v131, v133
	global_store_dwordx4 v[142:143], v[130:133], off offset:64
	v_pk_mul_f32 v[86:87], v[86:87], v[184:185] op_sel_hi:[1,0]
	v_pk_mul_f32 v[88:89], v[88:89], v[184:185] op_sel_hi:[1,0]
	v_pk_mul_f32 v[78:79], v[78:79], v[184:185] op_sel_hi:[1,0]
	v_pk_mul_f32 v[80:81], v[80:81], v[184:185] op_sel_hi:[1,0]
	v_cvt_pk_bf16_f32 v192, v86, v87
	v_cvt_pk_bf16_f32 v193, v88, v89
	v_cvt_pk_bf16_f32 v194, v78, v79
	v_cvt_pk_bf16_f32 v195, v80, v81
	s_nop 1
	v_permlane16_swap_b32_e32 v192, v194
	v_permlane16_swap_b32_e32 v193, v195
	global_store_dwordx4 v[142:143], v[192:195], off offset:256
	v_pk_mul_f32 v[70:71], v[70:71], v[184:185] op_sel_hi:[1,0]
	v_pk_mul_f32 v[72:73], v[72:73], v[184:185] op_sel_hi:[1,0]
	v_pk_mul_f32 v[66:67], v[66:67], v[184:185] op_sel_hi:[1,0]
	v_pk_mul_f32 v[68:69], v[68:69], v[184:185] op_sel_hi:[1,0]
	v_cvt_pk_bf16_f32 v130, v70, v71
	v_cvt_pk_bf16_f32 v131, v72, v73
	v_cvt_pk_bf16_f32 v132, v66, v67
	v_cvt_pk_bf16_f32 v133, v68, v69
	s_nop 1
	v_permlane16_swap_b32_e32 v130, v132
	v_permlane16_swap_b32_e32 v131, v133
	global_store_dwordx4 v[142:143], v[130:133], off offset:320
	v_pk_mul_f32 v[62:63], v[62:63], v[186:187] op_sel_hi:[1,0]
	v_pk_mul_f32 v[64:65], v[64:65], v[186:187] op_sel_hi:[1,0]
	v_pk_mul_f32 v[58:59], v[58:59], v[186:187] op_sel_hi:[1,0]
	v_pk_mul_f32 v[60:61], v[60:61], v[186:187] op_sel_hi:[1,0]
	v_cvt_pk_bf16_f32 v192, v62, v63
	v_cvt_pk_bf16_f32 v193, v64, v65
	v_cvt_pk_bf16_f32 v194, v58, v59
	v_cvt_pk_bf16_f32 v195, v60, v61
	s_nop 1
	v_permlane16_swap_b32_e32 v192, v194
	v_permlane16_swap_b32_e32 v193, v195
	global_store_dwordx4 v[144:145], v[192:195], off
	v_pk_mul_f32 v[54:55], v[54:55], v[186:187] op_sel_hi:[1,0]
	v_pk_mul_f32 v[56:57], v[56:57], v[186:187] op_sel_hi:[1,0]
	v_pk_mul_f32 v[46:47], v[46:47], v[186:187] op_sel_hi:[1,0]
	v_pk_mul_f32 v[48:49], v[48:49], v[186:187] op_sel_hi:[1,0]
	v_cvt_pk_bf16_f32 v130, v54, v55
	v_cvt_pk_bf16_f32 v131, v56, v57
	v_cvt_pk_bf16_f32 v132, v46, v47
	v_cvt_pk_bf16_f32 v133, v48, v49
	s_nop 1
	v_permlane16_swap_b32_e32 v130, v132
	v_permlane16_swap_b32_e32 v131, v133
	global_store_dwordx4 v[144:145], v[130:133], off offset:64
	v_pk_mul_f32 v[50:51], v[50:51], v[186:187] op_sel_hi:[1,0]
	v_pk_mul_f32 v[52:53], v[52:53], v[186:187] op_sel_hi:[1,0]
	v_pk_mul_f32 v[42:43], v[42:43], v[186:187] op_sel_hi:[1,0]
	v_pk_mul_f32 v[44:45], v[44:45], v[186:187] op_sel_hi:[1,0]
	v_cvt_pk_bf16_f32 v192, v50, v51
	v_cvt_pk_bf16_f32 v193, v52, v53
	v_cvt_pk_bf16_f32 v194, v42, v43
	v_cvt_pk_bf16_f32 v195, v44, v45
	s_nop 1
	v_permlane16_swap_b32_e32 v192, v194
	v_permlane16_swap_b32_e32 v193, v195
	global_store_dwordx4 v[144:145], v[192:195], off offset:256
	v_pk_mul_f32 v[38:39], v[38:39], v[186:187] op_sel_hi:[1,0]
	v_pk_mul_f32 v[40:41], v[40:41], v[186:187] op_sel_hi:[1,0]
	v_pk_mul_f32 v[34:35], v[34:35], v[186:187] op_sel_hi:[1,0]
	v_pk_mul_f32 v[36:37], v[36:37], v[186:187] op_sel_hi:[1,0]
	v_cvt_pk_bf16_f32 v130, v38, v39
	v_cvt_pk_bf16_f32 v131, v40, v41
	v_cvt_pk_bf16_f32 v132, v34, v35
	v_cvt_pk_bf16_f32 v133, v36, v37
	s_nop 1
	v_permlane16_swap_b32_e32 v130, v132
	v_permlane16_swap_b32_e32 v131, v133
	global_store_dwordx4 v[144:145], v[130:133], off offset:320
	v_pk_mul_f32 v[30:31], v[30:31], v[188:189] op_sel_hi:[1,0]
	v_pk_mul_f32 v[32:33], v[32:33], v[188:189] op_sel_hi:[1,0]
	v_pk_mul_f32 v[26:27], v[26:27], v[188:189] op_sel_hi:[1,0]
	v_pk_mul_f32 v[28:29], v[28:29], v[188:189] op_sel_hi:[1,0]
	v_cvt_pk_bf16_f32 v192, v30, v31
	v_cvt_pk_bf16_f32 v193, v32, v33
	v_cvt_pk_bf16_f32 v194, v26, v27
	v_cvt_pk_bf16_f32 v195, v28, v29
	s_nop 1
	v_permlane16_swap_b32_e32 v192, v194
	v_permlane16_swap_b32_e32 v193, v195
	global_store_dwordx4 v[146:147], v[192:195], off
	v_pk_mul_f32 v[22:23], v[22:23], v[188:189] op_sel_hi:[1,0]
	v_pk_mul_f32 v[24:25], v[24:25], v[188:189] op_sel_hi:[1,0]
	v_pk_mul_f32 v[14:15], v[14:15], v[188:189] op_sel_hi:[1,0]
	v_pk_mul_f32 v[16:17], v[16:17], v[188:189] op_sel_hi:[1,0]
	v_cvt_pk_bf16_f32 v130, v22, v23
	v_cvt_pk_bf16_f32 v131, v24, v25
	v_cvt_pk_bf16_f32 v132, v14, v15
	v_cvt_pk_bf16_f32 v133, v16, v17
	s_nop 1
	v_permlane16_swap_b32_e32 v130, v132
	v_permlane16_swap_b32_e32 v131, v133
	global_store_dwordx4 v[146:147], v[130:133], off offset:64
	v_pk_mul_f32 v[18:19], v[18:19], v[188:189] op_sel_hi:[1,0]
	v_pk_mul_f32 v[20:21], v[20:21], v[188:189] op_sel_hi:[1,0]
	v_pk_mul_f32 v[10:11], v[10:11], v[188:189] op_sel_hi:[1,0]
	v_pk_mul_f32 v[12:13], v[12:13], v[188:189] op_sel_hi:[1,0]
	v_cvt_pk_bf16_f32 v192, v18, v19
	v_cvt_pk_bf16_f32 v193, v20, v21
	v_cvt_pk_bf16_f32 v194, v10, v11
	v_cvt_pk_bf16_f32 v195, v12, v13
	s_nop 1
	v_permlane16_swap_b32_e32 v192, v194
	v_permlane16_swap_b32_e32 v193, v195
	global_store_dwordx4 v[146:147], v[192:195], off offset:256
	v_pk_mul_f32 v[6:7], v[6:7], v[188:189] op_sel_hi:[1,0]
	v_pk_mul_f32 v[8:9], v[8:9], v[188:189] op_sel_hi:[1,0]
	v_pk_mul_f32 v[2:3], v[2:3], v[188:189] op_sel_hi:[1,0]
	v_pk_mul_f32 v[4:5], v[4:5], v[188:189] op_sel_hi:[1,0]
	v_cvt_pk_bf16_f32 v130, v6, v7
	v_cvt_pk_bf16_f32 v131, v8, v9
	v_cvt_pk_bf16_f32 v132, v2, v3
	v_cvt_pk_bf16_f32 v133, v4, v5
	s_nop 1
	v_permlane16_swap_b32_e32 v130, v132
	v_permlane16_swap_b32_e32 v131, v133
	global_store_dwordx4 v[146:147], v[130:133], off offset:320
	s_branch .LBB0_1100
; __device__ __forceinline__ uint32_t pack2(float a, float b) { return (uint32_t)f2bf(a) | ((uint32_t)f2bf(b) << 16); }
;     ...
;       for (int bj = 0; bj < 2; ++bj) for (int nn = 0; nn < 2; ++nn) {
;         const long tok = bcol + bj * HALF + wc * 32 + nn * 16 + efr;
;         const float rs = rstd8(ssq_in + tok * 8);
;         for (int ai = 0; ai < 2; ++ai) for (int m = 0; m < 4; ++m) {
;           f32x4 a = acc[ai][bj][m][nn];
;           const int n = brow + ai * HALF + wr * 64 + m * 16 + efq * 4;
;           for (int j = 0; j < 4; ++j) a[j] *= rs;
;           if (EPI == EPI_SQRELU) { for (int j = 0; j < 4; ++j) { float r = fmaxf(a[j], 0.f); a[j] = r * r; } }
;           if (EPI == EPI_INPROJ && brow >= ZXLD) {
;             if (n < ZXLD + 32) *(float4*)(outf + tok * 32 + (n - ZXLD)) = make_float4(a[0], a[1], a[2], a[3]);
;           } else {
;             uint2 pk; pk.x = pack2(a[0], a[1]); pk.y = pack2(a[2], a[3]);
;             *(uint2*)(outb + tok * ldo + n) = pk;
;           }
;         }
.Lmy_inproj_slow:
	v_mov_b32_e32 v130, v0
	s_cmpk_lt_i32 s12, 0x1800
	v_and_b32_e32 v131, 15, v130
	v_add3_u32 v132, s10, v201, v131
	v_ashrrev_i32_e32 v133, 31, v132
	v_lshlrev_b64 v[134:135], 5, v[132:133]
	v_lshl_add_u64 v[138:139], s[20:21], 0, v[134:135]
	global_load_dwordx4 v[134:137], v[138:139], off offset:16
	s_nop 0
	global_load_dwordx4 v[138:141], v[138:139], off
	v_ashrrev_i32_e32 v130, 2, v130
	v_and_b32_e32 v130, -4, v130
	v_add3_u32 v130, s12, v200, v130
	s_cselect_b64 s[12:13], -1, 0
	s_waitcnt vmcnt(1)
	v_mov_b32_e32 v143, v134
	s_waitcnt vmcnt(0)
	v_mov_b32_e32 v142, v138
	v_mov_b32_e32 v134, v139
	v_mov_b32_e32 v138, v140
	v_mov_b32_e32 v139, v136
	v_mov_b32_e32 v136, v141
	v_pk_add_f32 v[134:135], v[142:143], v[134:135]
	v_pk_add_f32 v[136:137], v[138:139], v[136:137]
	s_nop 0
	v_pk_add_f32 v[134:135], v[134:135], v[136:137]
	v_mov_b64_e32 v[136:137], s[80:81]
	v_add_f32_e32 v131, v134, v135
	v_fmamk_f32 v131, v131, 0x3a800000, v225
	v_cmp_gt_f32_e32 vcc, s96, v131
	v_mul_f32_e32 v134, 0x4b800000, v131
	v_mad_i64_i32 v[136:137], s[10:11], v132, s3, v[136:137]
	v_cndmask_b32_e32 v131, v131, v134, vcc
	v_rsq_f32_e32 v131, v131
	s_mov_b64 s[10:11], -1
	v_mul_f32_e32 v134, 0x45800000, v131
	v_cndmask_b32_e32 v134, v131, v134, vcc
	v_pk_mul_f32 v[126:127], v[126:127], v[134:135] op_sel_hi:[1,0]
	v_pk_mul_f32 v[128:129], v[128:129], v[134:135] op_sel_hi:[1,0]
	s_and_b64 vcc, exec, s[12:13]
	v_ashrrev_i32_e32 v131, 31, v130
	s_cbranch_vccz .LBB0_1127
	v_cvt_pk_bf16_f32 v140, v127, v129
	v_cvt_pk_bf16_f32 v135, v126, v128
	v_and_b32_e32 v141, 0xffff0000, v140
	v_lshlrev_b32_e32 v140, 16, v140
	v_lshl_add_u64 v[138:139], v[130:131], 1, v[136:137]
	v_or_b32_sdwa v141, v141, v135 dst_sel:DWORD dst_unused:UNUSED_PAD src0_sel:DWORD src1_sel:WORD_1
	v_or_b32_sdwa v140, v140, v135 dst_sel:DWORD dst_unused:UNUSED_PAD src0_sel:DWORD src1_sel:WORD_0
	global_store_dwordx2 v[138:139], v[140:141], off
	s_mov_b64 s[10:11], 0
